# P6 prompt units: Q fragments of the S=KQ^T loop loaded one iteration ahead into spare registers (first iteration behind the K staging loads)
# baseline (speedup 1.0000x reference)
.LBB0_1162:
	s_lshl_b32 s14, s55, 2
	s_and_b32 s14, s14, 28
	s_ashr_i32 s23, s55, 6
	s_add_i32 s16, s14, s23
	s_ashr_i32 s17, s16, 31
	s_lshl_b64 s[18:19], s[16:17], 17
	v_lshl_add_u64 v[56:57], v[140:141], 0, s[18:19]
	v_mov_b32_e32 v157, v139
	v_mov_b32_e32 v179, v139
	v_mov_b32_e32 v159, v139
	v_lshlrev_b32_e32 v180, 1, v142
	v_mov_b32_e32 v181, v139
	v_mov_b32_e32 v161, v139
	v_lshlrev_b32_e32 v182, 1, v144
	v_mov_b32_e32 v183, v139
	v_mov_b32_e32 v163, v139
	v_lshlrev_b32_e32 v184, 1, v146
	v_mov_b32_e32 v185, v139
	v_mov_b32_e32 v165, v139
	v_lshlrev_b32_e32 v186, 1, v148
	v_mov_b32_e32 v187, v139
	v_mov_b32_e32 v167, v139
	v_lshlrev_b32_e32 v188, 1, v150
	v_mov_b32_e32 v189, v139
	v_mov_b32_e32 v169, v139
	v_lshlrev_b32_e32 v190, 1, v152
	v_mov_b32_e32 v191, v139
	v_lshl_add_u64 v[0:1], v[56:57], 0, v[172:173]
	v_lshl_add_u64 v[4:5], v[56:57], 0, v[176:177]
	v_lshl_add_u64 v[8:9], v[56:57], 0, v[156:157]
	v_lshl_add_u64 v[12:13], v[56:57], 0, v[178:179]
	v_lshl_add_u64 v[16:17], v[56:57], 0, v[158:159]
	v_lshl_add_u64 v[20:21], v[56:57], 0, v[180:181]
	v_lshl_add_u64 v[24:25], v[56:57], 0, v[160:161]
	v_lshl_add_u64 v[28:29], v[56:57], 0, v[182:183]
	v_lshl_add_u64 v[32:33], v[56:57], 0, v[162:163]
	v_lshl_add_u64 v[36:37], v[56:57], 0, v[184:185]
	v_lshl_add_u64 v[40:41], v[56:57], 0, v[164:165]
	v_lshl_add_u64 v[44:45], v[56:57], 0, v[186:187]
	v_lshl_add_u64 v[48:49], v[56:57], 0, v[166:167]
	v_lshl_add_u64 v[52:53], v[56:57], 0, v[188:189]
	v_lshl_add_u64 v[58:59], v[56:57], 0, v[168:169]
	v_lshl_add_u64 v[60:61], v[56:57], 0, v[190:191]
	global_load_dwordx4 v[0:3], v[0:1], off
	s_nop 0
	global_load_dwordx4 v[4:7], v[4:5], off
	s_nop 0
	global_load_dwordx4 v[8:11], v[8:9], off
	s_nop 0
	global_load_dwordx4 v[12:15], v[12:13], off
	s_nop 0
	global_load_dwordx4 v[16:19], v[16:17], off
	s_nop 0
	global_load_dwordx4 v[20:23], v[20:21], off
	s_nop 0
	global_load_dwordx4 v[24:27], v[24:25], off
	s_nop 0
	global_load_dwordx4 v[28:31], v[28:29], off
	s_nop 0
	global_load_dwordx4 v[32:35], v[32:33], off
	s_nop 0
	global_load_dwordx4 v[36:39], v[36:37], off
	s_nop 0
	global_load_dwordx4 v[40:43], v[40:41], off
	s_nop 0
	global_load_dwordx4 v[44:47], v[44:45], off
	s_nop 0
	global_load_dwordx4 v[48:51], v[48:49], off
	s_nop 0
	global_load_dwordx4 v[52:55], v[52:53], off
	s_nop 0
	global_load_dwordx4 v[56:59], v[58:59], off
	s_nop 0
	global_load_dwordx4 v[60:63], v[60:61], off
	v_readfirstlane_b32 s56, v128
	s_lshr_b32 s18, s56, 1
	s_and_b32 s33, s18, 0x7fffffe0
	s_ashr_i32 s18, s16, 2
	s_ashr_i32 s19, s18, 31
	s_and_b32 s14, s40, 0x700
	s_lshl_b64 s[36:37], s[16:17], 16
	s_lshl_b64 s[16:17], s[18:19], 11
	s_bfe_u32 s57, s40, 0x30008
	s_or_b32 s14, s16, s14
	s_add_u32 s16, s14, s33
	s_addc_u32 s17, s17, 0
	s_lshl_b32 s14, s23, 9
	s_and_b32 s14, s14, 0x600
	s_add_u32 s38, s42, s14
	s_addc_u32 s39, s43, 0
	s_mov_b32 s58, s15
	v_ashrrev_i32_e32 v248, 5, v195
	v_and_b32_e32 v250, 31, v195
	v_mov_b32_e32 v251, 0
	v_lshlrev_b32_e32 v248, 3, v248
	v_lshl_add_u64 v[250:251], s[16:17], 0, v[250:251]
	v_ashrrev_i32_e32 v249, 31, v248
	v_lshlrev_b64 v[250:251], 11, v[250:251]
	v_lshl_add_u64 v[248:249], v[248:249], 1, v[250:251]
	v_lshl_add_u64 v[252:253], s[38:39], 0, v[248:249]
	global_load_dwordx4 v[232:235], v[252:253], off offset:-64
	global_load_dwordx4 v[236:239], v[252:253], off offset:-32
	global_load_dwordx4 v[240:243], v[252:253], off
	global_load_dwordx4 v[244:247], v[252:253], off offset:32
	v_mov_b32_e32 v112, v139
	v_mov_b32_e32 v113, v139
	v_mov_b32_e32 v114, v139
	v_mov_b32_e32 v115, v139
	v_mov_b32_e32 v116, v139
	v_mov_b32_e32 v117, v139
	v_mov_b32_e32 v118, v139
	v_mov_b32_e32 v119, v139
	v_mov_b32_e32 v120, v139
	v_mov_b32_e32 v121, v139
	v_mov_b32_e32 v122, v139
	v_mov_b32_e32 v123, v139
	v_mov_b32_e32 v124, v139
	v_mov_b32_e32 v125, v139
	v_mov_b32_e32 v126, v139
	v_mov_b32_e32 v127, v139
	v_mov_b32_e32 v96, v139
	v_mov_b32_e32 v97, v139
	v_mov_b32_e32 v98, v139
	s_waitcnt vmcnt(19)
	ds_write_b128 v137, v[0:3]
	s_waitcnt vmcnt(18)
	ds_write_b128 v197, v[4:7]
	s_waitcnt vmcnt(17)
	ds_write_b128 v137, v[8:11] offset:8192
	s_waitcnt vmcnt(16)
	ds_write_b128 v198, v[12:15]
	s_waitcnt vmcnt(15)
	ds_write_b128 v137, v[16:19] offset:16384
	s_waitcnt vmcnt(14)
	ds_write_b128 v199, v[20:23]
	s_waitcnt vmcnt(13)
	ds_write_b128 v137, v[24:27] offset:24576
	s_waitcnt vmcnt(12)
	ds_write_b128 v200, v[28:31]
	s_waitcnt vmcnt(11)
	ds_write_b128 v137, v[32:35] offset:32768
	s_waitcnt vmcnt(10)
	ds_write_b128 v201, v[36:39]
	s_waitcnt vmcnt(9)
	ds_write_b128 v137, v[40:43] offset:40960
	s_waitcnt vmcnt(8)
	ds_write_b128 v202, v[44:47]
	s_waitcnt vmcnt(7)
	ds_write_b128 v137, v[48:51] offset:49152
	s_waitcnt vmcnt(6)
	ds_write_b128 v203, v[52:55]
	s_waitcnt vmcnt(5)
	ds_write_b128 v137, v[56:59] offset:57344
	s_waitcnt vmcnt(4)
	ds_write_b128 v204, v[60:63]
	v_mov_b32_e32 v99, v139
	v_mov_b32_e32 v100, v139
	v_mov_b32_e32 v101, v139
	v_mov_b32_e32 v102, v139
	v_mov_b32_e32 v103, v139
	v_mov_b32_e32 v104, v139
	v_mov_b32_e32 v105, v139
	v_mov_b32_e32 v106, v139
	v_mov_b32_e32 v107, v139
	v_mov_b32_e32 v108, v139
	v_mov_b32_e32 v109, v139
	v_mov_b32_e32 v110, v139
	v_mov_b32_e32 v111, v139
	v_mov_b32_e32 v80, v139
	v_mov_b32_e32 v81, v139
	v_mov_b32_e32 v82, v139
	v_mov_b32_e32 v83, v139
	v_mov_b32_e32 v84, v139
	v_mov_b32_e32 v85, v139
	v_mov_b32_e32 v86, v139
	v_mov_b32_e32 v87, v139
	v_mov_b32_e32 v88, v139
	v_mov_b32_e32 v89, v139
	v_mov_b32_e32 v90, v139
	v_mov_b32_e32 v91, v139
	v_mov_b32_e32 v92, v139
	v_mov_b32_e32 v93, v139
	v_mov_b32_e32 v94, v139
	v_mov_b32_e32 v95, v139
	v_mov_b32_e32 v64, v139
	v_mov_b32_e32 v65, v139
	v_mov_b32_e32 v66, v139
	v_mov_b32_e32 v67, v139
	v_mov_b32_e32 v68, v139
	v_mov_b32_e32 v69, v139
	v_mov_b32_e32 v70, v139
	v_mov_b32_e32 v71, v139
	v_mov_b32_e32 v72, v139
	v_mov_b32_e32 v73, v139
	v_mov_b32_e32 v74, v139
	v_mov_b32_e32 v75, v139
	v_mov_b32_e32 v76, v139
	v_mov_b32_e32 v77, v139
	v_mov_b32_e32 v78, v139
	v_mov_b32_e32 v79, v139
	v_mov_b32_e32 v48, v139
	v_mov_b32_e32 v49, v139
	v_mov_b32_e32 v50, v139
	v_mov_b32_e32 v51, v139
	v_mov_b32_e32 v52, v139
	v_mov_b32_e32 v53, v139
	v_mov_b32_e32 v54, v139
	v_mov_b32_e32 v55, v139
	v_mov_b32_e32 v56, v139
	v_mov_b32_e32 v57, v139
	v_mov_b32_e32 v58, v139
	v_mov_b32_e32 v59, v139
	v_mov_b32_e32 v60, v139
	v_mov_b32_e32 v61, v139
	v_mov_b32_e32 v62, v139
	v_mov_b32_e32 v63, v139
	v_mov_b32_e32 v32, v139
	v_mov_b32_e32 v33, v139
	v_mov_b32_e32 v34, v139
	v_mov_b32_e32 v35, v139
	v_mov_b32_e32 v36, v139
	v_mov_b32_e32 v37, v139
	v_mov_b32_e32 v38, v139
	v_mov_b32_e32 v39, v139
	v_mov_b32_e32 v40, v139
	v_mov_b32_e32 v41, v139
	v_mov_b32_e32 v42, v139
	v_mov_b32_e32 v43, v139
	v_mov_b32_e32 v44, v139
	v_mov_b32_e32 v45, v139
	v_mov_b32_e32 v46, v139
	v_mov_b32_e32 v47, v139
	v_mov_b32_e32 v16, v139
	v_mov_b32_e32 v17, v139
	v_mov_b32_e32 v18, v139
	v_mov_b32_e32 v19, v139
	v_mov_b32_e32 v20, v139
	v_mov_b32_e32 v21, v139
	v_mov_b32_e32 v22, v139
	v_mov_b32_e32 v23, v139
	v_mov_b32_e32 v24, v139
	v_mov_b32_e32 v25, v139
	v_mov_b32_e32 v26, v139
	v_mov_b32_e32 v27, v139
	v_mov_b32_e32 v28, v139
	v_mov_b32_e32 v29, v139
	v_mov_b32_e32 v30, v139
	v_mov_b32_e32 v31, v139
	v_mov_b32_e32 v0, v139
	v_mov_b32_e32 v1, v139
	v_mov_b32_e32 v2, v139
	v_mov_b32_e32 v3, v139
	v_mov_b32_e32 v4, v139
	v_mov_b32_e32 v5, v139
	v_mov_b32_e32 v6, v139
	v_mov_b32_e32 v7, v139
	v_mov_b32_e32 v8, v139
	v_mov_b32_e32 v9, v139
	v_mov_b32_e32 v10, v139
	v_mov_b32_e32 v11, v139
	v_mov_b32_e32 v12, v139
	v_mov_b32_e32 v13, v139
	v_mov_b32_e32 v14, v139
	v_mov_b32_e32 v15, v139
	s_waitcnt lgkmcnt(0)
	s_barrier
.LBB0_1163:
	v_mov_b32_e32 v159, v195
	s_nop 0
	v_ashrrev_i32_e32 v157, 5, v159
	v_and_b32_e32 v138, 31, v159
	v_lshlrev_b32_e32 v206, 3, v157
	v_lshl_add_u64 v[208:209], s[16:17], 0, v[138:139]
	v_ashrrev_i32_e32 v207, 31, v206
	v_lshlrev_b64 v[208:209], 11, v[208:209]
	v_lshl_add_u64 v[206:207], v[206:207], 1, v[208:209]
	v_lshl_add_u64 v[222:223], s[38:39], 0, v[206:207]
	s_waitcnt vmcnt(0)
	v_mov_b32_e32 v206, v232
	v_mov_b32_e32 v207, v233
	v_mov_b32_e32 v208, v234
	v_mov_b32_e32 v209, v235
	v_mov_b32_e32 v210, v236
	v_mov_b32_e32 v211, v237
	v_mov_b32_e32 v212, v238
	v_mov_b32_e32 v213, v239
	v_mov_b32_e32 v224, v240
	v_mov_b32_e32 v225, v241
	v_mov_b32_e32 v226, v242
	v_mov_b32_e32 v227, v243
	v_mov_b32_e32 v228, v244
	v_mov_b32_e32 v229, v245
	v_mov_b32_e32 v230, v246
	v_mov_b32_e32 v231, v247
	s_cmp_eq_u32 s58, 24
	s_cbranch_scc1 .Lp6_qpf_last
	global_load_dwordx4 v[232:235], v[222:223], off offset:64
	global_load_dwordx4 v[236:239], v[222:223], off offset:96
	global_load_dwordx4 v[240:243], v[222:223], off offset:128
	global_load_dwordx4 v[244:247], v[222:223], off offset:160
.Lp6_qpf_last:
	v_lshlrev_b32_e32 v161, 2, v159
	v_add_u32_e32 v163, s58, v157
	v_bfe_u32 v159, v159, 2, 2
	v_and_b32_e32 v161, 12, v161
	v_lshlrev_b32_e32 v165, 12, v163
	v_and_b32_e32 v167, 15, v163
	v_and_b32_e32 v165, 0xffff0000, v165
	v_bitop3_b32 v167, v161, v167, v159 bitop3:0x36
	v_lshlrev_b32_e32 v138, 8, v138
	v_add_u32_e32 v165, 0, v165
	v_lshlrev_b32_e32 v167, 4, v167
	v_add3_u32 v165, v165, v167, v138
	ds_read_b128 v[214:217], v165
	ds_read_b128 v[218:221], v165 offset:8192
	v_or_b32_e32 v159, v161, v159
	v_add_u32_e32 v161, 2, v163
	s_add_i32 s58, s58, 8
	s_add_u32 s38, s38, 0x80
	s_addc_u32 s39, s39, 0
	s_cmp_eq_u32 s58, 32
	s_waitcnt lgkmcnt(1)
	v_mfma_f32_32x32x16_bf16 v[112:127], v[214:217], v[206:209], v[112:127]
	s_waitcnt lgkmcnt(0)
	v_mfma_f32_32x32x16_bf16 v[96:111], v[218:221], v[206:209], v[96:111]
	ds_read_b128 v[214:217], v165 offset:16384
	ds_read_b128 v[218:221], v165 offset:24576
	s_waitcnt lgkmcnt(1)
	v_mfma_f32_32x32x16_bf16 v[80:95], v[214:217], v[206:209], v[80:95]
	s_waitcnt lgkmcnt(0)
	v_mfma_f32_32x32x16_bf16 v[64:79], v[218:221], v[206:209], v[64:79]
	ds_read_b128 v[214:217], v165 offset:32768
	ds_read_b128 v[218:221], v165 offset:40960
	s_waitcnt lgkmcnt(1)
	v_mfma_f32_32x32x16_bf16 v[48:63], v[214:217], v[206:209], v[48:63]
	s_waitcnt lgkmcnt(0)
	v_mfma_f32_32x32x16_bf16 v[32:47], v[218:221], v[206:209], v[32:47]
	ds_read_b128 v[214:217], v165 offset:49152
	ds_read_b128 v[218:221], v165 offset:57344
	v_lshlrev_b32_e32 v165, 12, v161
	v_bitop3_b32 v161, v161, v159, 15 bitop3:0x6c
	v_and_b32_e32 v165, 0xffff0000, v165
	v_lshlrev_b32_e32 v161, 4, v161
	v_add_u32_e32 v165, 0, v165
	v_add3_u32 v161, v165, v161, v138
	s_waitcnt lgkmcnt(1)
	v_mfma_f32_32x32x16_bf16 v[16:31], v[214:217], v[206:209], v[16:31]
	v_add_u32_e32 v165, 4, v163
	v_lshlrev_b32_e32 v167, 12, v165
	v_bitop3_b32 v165, v165, v159, 15 bitop3:0x6c
	v_and_b32_e32 v167, 0xffff0000, v167
	v_lshlrev_b32_e32 v165, 4, v165
	s_waitcnt lgkmcnt(0)
	v_mfma_f32_32x32x16_bf16 v[0:15], v[218:221], v[206:209], v[0:15]
	ds_read_b128 v[206:209], v161
	ds_read_b128 v[214:217], v161 offset:8192
	s_waitcnt lgkmcnt(1)
	v_mfma_f32_32x32x16_bf16 v[112:127], v[206:209], v[210:213], v[112:127]
	s_waitcnt lgkmcnt(0)
	v_mfma_f32_32x32x16_bf16 v[96:111], v[214:217], v[210:213], v[96:111]
	ds_read_b128 v[206:209], v161 offset:16384
	ds_read_b128 v[214:217], v161 offset:24576
	s_waitcnt lgkmcnt(1)
	v_mfma_f32_32x32x16_bf16 v[80:95], v[206:209], v[210:213], v[80:95]
	s_waitcnt lgkmcnt(0)
	v_mfma_f32_32x32x16_bf16 v[64:79], v[214:217], v[210:213], v[64:79]
	ds_read_b128 v[206:209], v161 offset:32768
	ds_read_b128 v[214:217], v161 offset:40960
	s_waitcnt lgkmcnt(1)
	v_mfma_f32_32x32x16_bf16 v[48:63], v[206:209], v[210:213], v[48:63]
	s_waitcnt lgkmcnt(0)
	v_mfma_f32_32x32x16_bf16 v[32:47], v[214:217], v[210:213], v[32:47]
	ds_read_b128 v[206:209], v161 offset:49152
	ds_read_b128 v[214:217], v161 offset:57344
	v_add_u32_e32 v161, 0, v167
	v_add3_u32 v161, v161, v165, v138
	s_waitcnt lgkmcnt(1)
	v_mfma_f32_32x32x16_bf16 v[16:31], v[206:209], v[210:213], v[16:31]
	s_waitcnt lgkmcnt(0)
	v_mfma_f32_32x32x16_bf16 v[0:15], v[214:217], v[210:213], v[0:15]
	ds_read_b128 v[210:213], v161
	ds_read_b128 v[214:217], v161 offset:8192
	s_waitcnt lgkmcnt(1)
	v_mfma_f32_32x32x16_bf16 v[112:127], v[210:213], v[224:227], v[112:127]
	s_waitcnt lgkmcnt(0)
	v_mfma_f32_32x32x16_bf16 v[96:111], v[214:217], v[224:227], v[96:111]
	ds_read_b128 v[210:213], v161 offset:16384
	ds_read_b128 v[214:217], v161 offset:24576
	s_waitcnt lgkmcnt(1)
	v_mfma_f32_32x32x16_bf16 v[80:95], v[210:213], v[224:227], v[80:95]
	s_waitcnt lgkmcnt(0)
	v_mfma_f32_32x32x16_bf16 v[64:79], v[214:217], v[224:227], v[64:79]
	ds_read_b128 v[210:213], v161 offset:32768
	ds_read_b128 v[214:217], v161 offset:40960
	s_waitcnt lgkmcnt(1)
	v_mfma_f32_32x32x16_bf16 v[48:63], v[210:213], v[224:227], v[48:63]
	s_waitcnt lgkmcnt(0)
	v_mfma_f32_32x32x16_bf16 v[32:47], v[214:217], v[224:227], v[32:47]
	ds_read_b128 v[210:213], v161 offset:49152
	ds_read_b128 v[214:217], v161 offset:57344
	v_add_u32_e32 v161, 6, v163
	v_lshlrev_b32_e32 v163, 12, v161
	v_bitop3_b32 v159, v161, v159, 15 bitop3:0x6c
	v_and_b32_e32 v161, 0xffff0000, v163
	v_lshlrev_b32_e32 v159, 4, v159
	v_add_u32_e32 v161, 0, v161
	v_add3_u32 v138, v161, v159, v138
	s_waitcnt lgkmcnt(1)
	v_mfma_f32_32x32x16_bf16 v[16:31], v[210:213], v[224:227], v[16:31]
	s_waitcnt lgkmcnt(0)
	v_mfma_f32_32x32x16_bf16 v[0:15], v[214:217], v[224:227], v[0:15]
	ds_read_b128 v[206:209], v138
	ds_read_b128 v[210:213], v138 offset:8192
	s_waitcnt lgkmcnt(1)
	v_mfma_f32_32x32x16_bf16 v[112:127], v[206:209], v[228:231], v[112:127]
	s_waitcnt lgkmcnt(0)
	v_mfma_f32_32x32x16_bf16 v[96:111], v[210:213], v[228:231], v[96:111]
	ds_read_b128 v[206:209], v138 offset:16384
	ds_read_b128 v[210:213], v138 offset:24576
	s_waitcnt lgkmcnt(1)
	v_mfma_f32_32x32x16_bf16 v[80:95], v[206:209], v[228:231], v[80:95]
	s_waitcnt lgkmcnt(0)
	v_mfma_f32_32x32x16_bf16 v[64:79], v[210:213], v[228:231], v[64:79]
	ds_read_b128 v[206:209], v138 offset:32768
	ds_read_b128 v[210:213], v138 offset:40960
	s_waitcnt lgkmcnt(1)
	v_mfma_f32_32x32x16_bf16 v[48:63], v[206:209], v[228:231], v[48:63]
	s_waitcnt lgkmcnt(0)
	v_mfma_f32_32x32x16_bf16 v[32:47], v[210:213], v[228:231], v[32:47]
	ds_read_b128 v[206:209], v138 offset:49152
	ds_read_b128 v[210:213], v138 offset:57344
	s_waitcnt lgkmcnt(1)
	v_mfma_f32_32x32x16_bf16 v[16:31], v[206:209], v[228:231], v[16:31]
	s_waitcnt lgkmcnt(0)
	v_mfma_f32_32x32x16_bf16 v[0:15], v[210:213], v[228:231], v[0:15]
	s_cbranch_scc0 .LBB0_1163
	v_max3_f32 v138, v112, s45, v113
	v_max3_f32 v138, v138, v114, v115
	v_max3_f32 v138, v138, v116, v117
	v_max3_f32 v138, v138, v118, v119
	v_max3_f32 v138, v138, v120, v121
	v_max3_f32 v138, v138, v122, v123
	v_max3_f32 v138, v138, v124, v125
	v_max3_f32 v138, v138, v126, v127
	v_max3_f32 v138, v138, v96, v97
	v_max3_f32 v138, v138, v98, v99
	v_max3_f32 v138, v138, v100, v101
	v_max3_f32 v138, v138, v102, v103
	v_max3_f32 v138, v138, v104, v105
	v_max3_f32 v138, v138, v106, v107
	v_max3_f32 v138, v138, v108, v109
	v_max3_f32 v138, v138, v110, v111
	v_max3_f32 v138, v138, v80, v81
	v_max3_f32 v138, v138, v82, v83
	v_max3_f32 v138, v138, v84, v85
	v_max3_f32 v138, v138, v86, v87
	v_max3_f32 v138, v138, v88, v89
	v_max3_f32 v138, v138, v90, v91
	v_max3_f32 v138, v138, v92, v93
	v_max3_f32 v138, v138, v94, v95
	v_max3_f32 v138, v138, v64, v65
	v_max3_f32 v138, v138, v66, v67
	v_max3_f32 v138, v138, v68, v69
	v_max3_f32 v138, v138, v70, v71
	v_max3_f32 v138, v138, v72, v73
	v_max3_f32 v138, v138, v74, v75
	v_max3_f32 v138, v138, v76, v77
	v_max3_f32 v138, v138, v78, v79
	v_max3_f32 v138, v138, v48, v49
	v_max3_f32 v138, v138, v50, v51
	v_max3_f32 v138, v138, v52, v53
	v_max3_f32 v138, v138, v54, v55
	v_max3_f32 v138, v138, v56, v57
	v_max3_f32 v138, v138, v58, v59
	v_max3_f32 v138, v138, v60, v61
	v_max3_f32 v138, v138, v62, v63
	v_max3_f32 v138, v138, v32, v33
	v_max3_f32 v138, v138, v34, v35
	v_max3_f32 v138, v138, v36, v37
	v_max3_f32 v138, v138, v38, v39
	v_max3_f32 v138, v138, v40, v41
	v_max3_f32 v138, v138, v42, v43
	v_max3_f32 v138, v138, v44, v45
	v_max3_f32 v138, v138, v46, v47
	v_max3_f32 v138, v138, v16, v17
	v_max3_f32 v138, v138, v18, v19
	v_max3_f32 v138, v138, v20, v21
	v_max3_f32 v138, v138, v22, v23
	v_max3_f32 v138, v138, v24, v25
	v_max3_f32 v138, v138, v26, v27
	v_max3_f32 v138, v138, v28, v29
	v_max3_f32 v138, v138, v30, v31
	v_max3_f32 v138, v138, v0, v1
	v_max3_f32 v138, v138, v2, v3
	v_max3_f32 v138, v138, v4, v5
	v_max3_f32 v138, v138, v6, v7
	v_max3_f32 v138, v138, v8, v9
	v_max3_f32 v138, v138, v10, v11
	v_max3_f32 v138, v138, v12, v13
	v_max3_f32 v161, v138, v14, v15
	v_and_b32_e32 v138, 64, v205
	v_xor_b32_e32 v159, 32, v205
	v_add_u32_e32 v163, 64, v138
	v_cmp_lt_i32_e32 vcc, v159, v163
	v_lshlrev_b32_e32 v211, 2, v157
	v_mov_b32_e32 v157, v139
	v_cndmask_b32_e32 v159, v205, v159, vcc
	v_lshlrev_b32_e32 v159, 2, v159
	ds_bpermute_b32 v163, v159, v161
	s_waitcnt lgkmcnt(0)
	s_barrier
	s_lshl_b32 s39, s57, 19
	v_max_f32_e32 v163, v163, v163
	v_max_f32_e32 v161, v161, v163
	v_sub_f32_e32 v112, v112, v161
	v_mul_f32_e32 v112, 0x3fb8aa3b, v112
	v_exp_f32_e32 v163, v112
	v_sub_f32_e32 v112, v113, v161
	v_mul_f32_e32 v112, 0x3fb8aa3b, v112
	v_exp_f32_e32 v165, v112
	v_sub_f32_e32 v112, v114, v161
	v_mul_f32_e32 v112, 0x3fb8aa3b, v112
	v_exp_f32_e32 v167, v112
	v_sub_f32_e32 v112, v115, v161
	v_mul_f32_e32 v112, 0x3fb8aa3b, v112
	v_exp_f32_e32 v169, v112
	v_sub_f32_e32 v112, v116, v161
	v_mul_f32_e32 v112, 0x3fb8aa3b, v112
	v_exp_f32_e32 v171, v112
	v_sub_f32_e32 v112, v117, v161
	v_mul_f32_e32 v112, 0x3fb8aa3b, v112
	v_exp_f32_e32 v175, v112
	v_sub_f32_e32 v112, v118, v161
	v_mul_f32_e32 v112, 0x3fb8aa3b, v112
	v_exp_f32_e32 v179, v112
	v_sub_f32_e32 v112, v119, v161
	v_mul_f32_e32 v112, 0x3fb8aa3b, v112
	v_exp_f32_e32 v181, v112
	v_sub_f32_e32 v112, v120, v161
	v_mul_f32_e32 v112, 0x3fb8aa3b, v112
	v_exp_f32_e32 v120, v112
	v_sub_f32_e32 v112, v121, v161
	v_mul_f32_e32 v112, 0x3fb8aa3b, v112
	v_exp_f32_e32 v121, v112
	v_sub_f32_e32 v112, v122, v161
	v_mul_f32_e32 v112, 0x3fb8aa3b, v112
	v_exp_f32_e32 v122, v112
	v_sub_f32_e32 v112, v123, v161
	v_mul_f32_e32 v112, 0x3fb8aa3b, v112
	v_bfe_u32 v114, v169, 16, 1
	v_exp_f32_e32 v123, v112
	v_sub_f32_e32 v112, v124, v161
	v_add3_u32 v117, v169, v114, s46
	v_bfe_u32 v114, v163, 16, 1
	v_mul_f32_e32 v112, 0x3fb8aa3b, v112
	v_add3_u32 v114, v163, v114, s46
	v_add_f32_e32 v163, 0, v163
	v_exp_f32_e32 v124, v112
	v_sub_f32_e32 v112, v125, v161
	v_add_f32_e32 v163, v165, v163
	v_mul_f32_e32 v112, 0x3fb8aa3b, v112
	v_add_f32_e32 v163, v167, v163
	v_exp_f32_e32 v125, v112
	v_sub_f32_e32 v112, v126, v161
	v_bfe_u32 v115, v165, 16, 1
	v_add_f32_e32 v163, v169, v163
	v_mul_f32_e32 v112, 0x3fb8aa3b, v112
	v_add3_u32 v116, v165, v115, s46
	v_bfe_u32 v115, v167, 16, 1
	v_bfe_u32 v118, v171, 16, 1
	v_add_f32_e32 v163, v171, v163
	v_exp_f32_e32 v126, v112
	v_sub_f32_e32 v112, v127, v161
	v_bfe_u32 v113, v175, 16, 1
	v_add3_u32 v118, v171, v118, s46
	v_add3_u32 v115, v167, v115, s46
	v_add_f32_e32 v163, v175, v163
	v_mul_f32_e32 v112, 0x3fb8aa3b, v112
	v_add3_u32 v113, v175, v113, s46
	v_bfe_u32 v119, v179, 16, 1
	v_lshrrev_b32_e32 v183, 16, v114
	v_lshrrev_b32_e32 v185, 16, v115
	v_lshrrev_b32_e32 v114, 16, v118
	v_bfe_u32 v118, v123, 16, 1
	v_add_f32_e32 v163, v179, v163
	v_exp_f32_e32 v127, v112
	v_bfe_u32 v112, v181, 16, 1
	v_add3_u32 v119, v179, v119, s46
	v_and_or_b32 v114, v113, s44, v114
	v_and_or_b32 v113, v117, s44, v185
	v_add3_u32 v185, v123, v118, s46
	v_bfe_u32 v118, v120, 16, 1
	v_add_f32_e32 v163, v181, v163
	v_sub_f32_e32 v96, v96, v161
	v_add3_u32 v112, v181, v112, s46
	v_lshrrev_b32_e32 v115, 16, v119
	v_bfe_u32 v119, v121, 16, 1
	v_add3_u32 v118, v120, v118, s46
	v_add_f32_e32 v120, v120, v163
	v_mul_f32_e32 v96, 0x3fb8aa3b, v96
	v_and_or_b32 v115, v112, s44, v115
	v_and_or_b32 v112, v116, s44, v183
	v_add3_u32 v183, v121, v119, s46
	v_add_f32_e32 v120, v121, v120
	v_exp_f32_e32 v121, v96
	v_sub_f32_e32 v96, v97, v161
	v_bfe_u32 v119, v122, 16, 1
	v_mul_f32_e32 v96, 0x3fb8aa3b, v96
	v_add3_u32 v119, v122, v119, s46
	v_add_f32_e32 v120, v122, v120
	v_exp_f32_e32 v122, v96
	v_sub_f32_e32 v96, v98, v161
	v_mul_f32_e32 v96, 0x3fb8aa3b, v96
	v_add_f32_e32 v120, v123, v120
	v_exp_f32_e32 v123, v96
	v_sub_f32_e32 v96, v99, v161
	v_bfe_u32 v187, v124, 16, 1
	v_mul_f32_e32 v96, 0x3fb8aa3b, v96
	v_add3_u32 v187, v124, v187, s46
	v_add_f32_e32 v120, v124, v120
	v_exp_f32_e32 v124, v96
	v_sub_f32_e32 v96, v100, v161
	v_bfe_u32 v117, v125, 16, 1
	v_mul_f32_e32 v96, 0x3fb8aa3b, v96
	v_add3_u32 v117, v125, v117, s46
	v_add_f32_e32 v120, v125, v120
	v_exp_f32_e32 v125, v96
	v_sub_f32_e32 v96, v101, v161
	v_bfe_u32 v189, v126, 16, 1
	v_mul_f32_e32 v96, 0x3fb8aa3b, v96
	v_add3_u32 v189, v126, v189, s46
	v_add_f32_e32 v120, v126, v120
	v_exp_f32_e32 v126, v96
	v_sub_f32_e32 v96, v102, v161
	v_bfe_u32 v116, v127, 16, 1
	v_mul_f32_e32 v96, 0x3fb8aa3b, v96
	v_add3_u32 v116, v127, v116, s46
	v_add_f32_e32 v120, v127, v120
	v_exp_f32_e32 v127, v96
	v_sub_f32_e32 v96, v103, v161
	v_mul_f32_e32 v96, 0x3fb8aa3b, v96
	v_exp_f32_e32 v163, v96
	v_sub_f32_e32 v96, v104, v161
	v_mul_f32_e32 v96, 0x3fb8aa3b, v96
	v_exp_f32_e32 v104, v96
	v_sub_f32_e32 v96, v105, v161
	v_mul_f32_e32 v96, 0x3fb8aa3b, v96
	v_exp_f32_e32 v105, v96
	v_sub_f32_e32 v96, v106, v161
	v_mul_f32_e32 v96, 0x3fb8aa3b, v96
	v_exp_f32_e32 v106, v96
	v_sub_f32_e32 v96, v107, v161
	v_mul_f32_e32 v96, 0x3fb8aa3b, v96
	v_exp_f32_e32 v107, v96
	v_sub_f32_e32 v96, v108, v161
	v_mul_f32_e32 v96, 0x3fb8aa3b, v96
	v_add_f32_e32 v120, v121, v120
	v_exp_f32_e32 v108, v96
	v_sub_f32_e32 v96, v109, v161
	v_add_f32_e32 v120, v122, v120
	v_mul_f32_e32 v96, 0x3fb8aa3b, v96
	v_add_f32_e32 v120, v123, v120
	v_exp_f32_e32 v109, v96
	v_sub_f32_e32 v96, v110, v161
	v_bfe_u32 v98, v124, 16, 1
	v_bfe_u32 v99, v122, 16, 1
	v_add_f32_e32 v120, v124, v120
	v_mul_f32_e32 v96, 0x3fb8aa3b, v96
	v_add3_u32 v100, v122, v99, s46
	v_add3_u32 v101, v124, v98, s46
	v_bfe_u32 v98, v121, 16, 1
	v_bfe_u32 v99, v123, 16, 1
	v_bfe_u32 v102, v125, 16, 1
	v_add_f32_e32 v120, v125, v120
	v_exp_f32_e32 v110, v96
	v_sub_f32_e32 v96, v111, v161
	v_bfe_u32 v97, v126, 16, 1
	v_add3_u32 v102, v125, v102, s46
	v_add3_u32 v99, v123, v99, s46
	v_add3_u32 v98, v121, v98, s46
	v_add_f32_e32 v120, v126, v120
	v_mul_f32_e32 v96, 0x3fb8aa3b, v96
	v_add3_u32 v97, v126, v97, s46
	v_bfe_u32 v103, v127, 16, 1
	v_lshrrev_b32_e32 v165, 16, v98
	v_lshrrev_b32_e32 v167, 16, v99
	v_lshrrev_b32_e32 v98, 16, v102
	v_bfe_u32 v102, v107, 16, 1
	v_add_f32_e32 v120, v127, v120
	v_exp_f32_e32 v111, v96
	v_bfe_u32 v96, v163, 16, 1
	v_add3_u32 v103, v127, v103, s46
	v_and_or_b32 v98, v97, s44, v98
	v_and_or_b32 v97, v101, s44, v167
	v_add3_u32 v167, v107, v102, s46
	v_bfe_u32 v102, v104, 16, 1
	v_add_f32_e32 v120, v163, v120
	v_sub_f32_e32 v80, v80, v161
	v_add3_u32 v96, v163, v96, s46
	v_lshrrev_b32_e32 v99, 16, v103
	v_bfe_u32 v103, v105, 16, 1
	v_add3_u32 v102, v104, v102, s46
	v_add_f32_e32 v104, v104, v120
	v_mul_f32_e32 v80, 0x3fb8aa3b, v80
	v_and_or_b32 v99, v96, s44, v99
	v_and_or_b32 v96, v100, s44, v165
	v_add3_u32 v165, v105, v103, s46
	v_add_f32_e32 v104, v105, v104
	v_exp_f32_e32 v105, v80
	v_sub_f32_e32 v80, v81, v161
	v_bfe_u32 v103, v106, 16, 1
	v_mul_f32_e32 v80, 0x3fb8aa3b, v80
	v_add3_u32 v103, v106, v103, s46
	v_add_f32_e32 v104, v106, v104
	v_exp_f32_e32 v106, v80
	v_sub_f32_e32 v80, v82, v161
	v_mul_f32_e32 v80, 0x3fb8aa3b, v80
	v_add_f32_e32 v104, v107, v104
	v_exp_f32_e32 v107, v80
	v_sub_f32_e32 v80, v83, v161
	v_bfe_u32 v169, v108, 16, 1
	v_mul_f32_e32 v80, 0x3fb8aa3b, v80
	v_add3_u32 v169, v108, v169, s46
	v_add_f32_e32 v104, v108, v104
	v_exp_f32_e32 v108, v80
	v_sub_f32_e32 v80, v84, v161
	v_bfe_u32 v101, v109, 16, 1
	v_mul_f32_e32 v80, 0x3fb8aa3b, v80
	v_add3_u32 v101, v109, v101, s46
	v_add_f32_e32 v104, v109, v104
	v_exp_f32_e32 v109, v80
	v_sub_f32_e32 v80, v85, v161
	v_bfe_u32 v171, v110, 16, 1
	v_mul_f32_e32 v80, 0x3fb8aa3b, v80
	v_add3_u32 v171, v110, v171, s46
	v_add_f32_e32 v104, v110, v104
	v_exp_f32_e32 v110, v80
	v_sub_f32_e32 v80, v86, v161
	v_bfe_u32 v100, v111, 16, 1
	v_mul_f32_e32 v80, 0x3fb8aa3b, v80
	v_add3_u32 v100, v111, v100, s46
	v_add_f32_e32 v104, v111, v104
	v_exp_f32_e32 v111, v80
	v_sub_f32_e32 v80, v87, v161
	v_mul_f32_e32 v80, 0x3fb8aa3b, v80
	v_exp_f32_e32 v120, v80
	v_sub_f32_e32 v80, v88, v161
	v_mul_f32_e32 v80, 0x3fb8aa3b, v80
	v_exp_f32_e32 v88, v80
	v_sub_f32_e32 v80, v89, v161
	v_mul_f32_e32 v80, 0x3fb8aa3b, v80
	v_exp_f32_e32 v89, v80
	v_sub_f32_e32 v80, v90, v161
	v_mul_f32_e32 v80, 0x3fb8aa3b, v80
	v_exp_f32_e32 v90, v80
	v_sub_f32_e32 v80, v91, v161
	v_mul_f32_e32 v80, 0x3fb8aa3b, v80
	v_exp_f32_e32 v91, v80
	v_sub_f32_e32 v80, v92, v161
	v_mul_f32_e32 v80, 0x3fb8aa3b, v80
	v_add_f32_e32 v104, v105, v104
	v_exp_f32_e32 v92, v80
	v_sub_f32_e32 v80, v93, v161
	v_add_f32_e32 v104, v106, v104
	v_mul_f32_e32 v80, 0x3fb8aa3b, v80
	v_add_f32_e32 v104, v107, v104
	v_exp_f32_e32 v93, v80
	v_sub_f32_e32 v80, v94, v161
	v_bfe_u32 v82, v108, 16, 1
	v_bfe_u32 v83, v106, 16, 1
	v_add_f32_e32 v104, v108, v104
	v_mul_f32_e32 v80, 0x3fb8aa3b, v80
	v_add3_u32 v84, v106, v83, s46
	v_add3_u32 v85, v108, v82, s46
	v_bfe_u32 v82, v105, 16, 1
	v_bfe_u32 v83, v107, 16, 1
	v_bfe_u32 v86, v109, 16, 1
	v_add_f32_e32 v104, v109, v104
	v_exp_f32_e32 v94, v80
	v_sub_f32_e32 v80, v95, v161
	v_bfe_u32 v81, v110, 16, 1
	v_add3_u32 v86, v109, v86, s46
	v_add3_u32 v83, v107, v83, s46
	v_add3_u32 v82, v105, v82, s46
	v_add_f32_e32 v104, v110, v104
	v_mul_f32_e32 v80, 0x3fb8aa3b, v80
	v_add3_u32 v81, v110, v81, s46
	v_bfe_u32 v87, v111, 16, 1
	v_lshrrev_b32_e32 v121, 16, v82
	v_lshrrev_b32_e32 v122, 16, v83
	v_lshrrev_b32_e32 v82, 16, v86
	v_bfe_u32 v86, v91, 16, 1
	v_add_f32_e32 v104, v111, v104
	v_exp_f32_e32 v95, v80
	v_bfe_u32 v80, v120, 16, 1
	v_add3_u32 v87, v111, v87, s46
	v_and_or_b32 v82, v81, s44, v82
	v_and_or_b32 v81, v85, s44, v122
	v_add3_u32 v122, v91, v86, s46
	v_bfe_u32 v86, v88, 16, 1
	v_add_f32_e32 v104, v120, v104
	v_sub_f32_e32 v64, v64, v161
	v_add3_u32 v80, v120, v80, s46
	v_lshrrev_b32_e32 v83, 16, v87
	v_bfe_u32 v87, v89, 16, 1
	v_add3_u32 v86, v88, v86, s46
	v_add_f32_e32 v88, v88, v104
	v_mul_f32_e32 v64, 0x3fb8aa3b, v64
	v_and_or_b32 v83, v80, s44, v83
	v_and_or_b32 v80, v84, s44, v121
	v_add3_u32 v121, v89, v87, s46
	v_add_f32_e32 v88, v89, v88
	v_exp_f32_e32 v89, v64
	v_sub_f32_e32 v64, v65, v161
	v_bfe_u32 v87, v90, 16, 1
	v_mul_f32_e32 v64, 0x3fb8aa3b, v64
	v_add3_u32 v87, v90, v87, s46
	v_add_f32_e32 v88, v90, v88
	v_exp_f32_e32 v90, v64
	v_sub_f32_e32 v64, v66, v161
	v_mul_f32_e32 v64, 0x3fb8aa3b, v64
	v_add_f32_e32 v88, v91, v88
	v_exp_f32_e32 v91, v64
	v_sub_f32_e32 v64, v67, v161
	v_bfe_u32 v123, v92, 16, 1
	v_mul_f32_e32 v64, 0x3fb8aa3b, v64
	v_add3_u32 v123, v92, v123, s46
	v_add_f32_e32 v88, v92, v88
	v_exp_f32_e32 v92, v64
	v_sub_f32_e32 v64, v68, v161
	v_bfe_u32 v85, v93, 16, 1
	v_mul_f32_e32 v64, 0x3fb8aa3b, v64
	v_add3_u32 v85, v93, v85, s46
	v_add_f32_e32 v88, v93, v88
	v_exp_f32_e32 v93, v64
	v_sub_f32_e32 v64, v69, v161
	v_bfe_u32 v124, v94, 16, 1
	v_mul_f32_e32 v64, 0x3fb8aa3b, v64
	v_add3_u32 v124, v94, v124, s46
	v_add_f32_e32 v88, v94, v88
	v_exp_f32_e32 v94, v64
	v_sub_f32_e32 v64, v70, v161
	v_bfe_u32 v84, v95, 16, 1
	v_mul_f32_e32 v64, 0x3fb8aa3b, v64
	v_add3_u32 v84, v95, v84, s46
	v_add_f32_e32 v88, v95, v88
	v_exp_f32_e32 v95, v64
	v_sub_f32_e32 v64, v71, v161
	v_mul_f32_e32 v64, 0x3fb8aa3b, v64
	v_exp_f32_e32 v104, v64
	v_sub_f32_e32 v64, v72, v161
	v_mul_f32_e32 v64, 0x3fb8aa3b, v64
	v_exp_f32_e32 v72, v64
	v_sub_f32_e32 v64, v73, v161
	v_mul_f32_e32 v64, 0x3fb8aa3b, v64
	v_exp_f32_e32 v73, v64
	v_sub_f32_e32 v64, v74, v161
	v_mul_f32_e32 v64, 0x3fb8aa3b, v64
	v_exp_f32_e32 v74, v64
	v_sub_f32_e32 v64, v75, v161
	v_mul_f32_e32 v64, 0x3fb8aa3b, v64
	v_exp_f32_e32 v75, v64
	v_sub_f32_e32 v64, v76, v161
	v_mul_f32_e32 v64, 0x3fb8aa3b, v64
	v_add_f32_e32 v88, v89, v88
	v_exp_f32_e32 v76, v64
	v_sub_f32_e32 v64, v77, v161
	v_add_f32_e32 v88, v90, v88
	v_mul_f32_e32 v64, 0x3fb8aa3b, v64
	v_add_f32_e32 v88, v91, v88
	v_exp_f32_e32 v77, v64
	v_sub_f32_e32 v64, v78, v161
	v_bfe_u32 v66, v92, 16, 1
	v_bfe_u32 v67, v90, 16, 1
	v_add_f32_e32 v88, v92, v88
	v_mul_f32_e32 v64, 0x3fb8aa3b, v64
	v_add3_u32 v68, v90, v67, s46
	v_add3_u32 v69, v92, v66, s46
	v_bfe_u32 v66, v89, 16, 1
	v_bfe_u32 v67, v91, 16, 1
	v_bfe_u32 v70, v93, 16, 1
	v_add_f32_e32 v88, v93, v88
	v_exp_f32_e32 v78, v64
	v_sub_f32_e32 v64, v79, v161
	v_bfe_u32 v65, v94, 16, 1
	v_add3_u32 v70, v93, v70, s46
	v_add3_u32 v67, v91, v67, s46
	v_add3_u32 v66, v89, v66, s46
	v_add_f32_e32 v88, v94, v88
	v_mul_f32_e32 v64, 0x3fb8aa3b, v64
	v_add3_u32 v65, v94, v65, s46
	v_bfe_u32 v71, v95, 16, 1
	v_lshrrev_b32_e32 v105, 16, v66
	v_lshrrev_b32_e32 v106, 16, v67
	v_lshrrev_b32_e32 v66, 16, v70
	v_bfe_u32 v70, v75, 16, 1
	v_add_f32_e32 v88, v95, v88
	v_exp_f32_e32 v79, v64
	v_bfe_u32 v64, v104, 16, 1
	v_add3_u32 v71, v95, v71, s46
	v_and_or_b32 v66, v65, s44, v66
	v_and_or_b32 v65, v69, s44, v106
	v_add3_u32 v106, v75, v70, s46
	v_bfe_u32 v70, v72, 16, 1
	v_add_f32_e32 v88, v104, v88
	v_sub_f32_e32 v48, v48, v161
	v_add3_u32 v64, v104, v64, s46
	v_lshrrev_b32_e32 v67, 16, v71
	v_bfe_u32 v71, v73, 16, 1
	v_add3_u32 v70, v72, v70, s46
	v_add_f32_e32 v72, v72, v88
	v_mul_f32_e32 v48, 0x3fb8aa3b, v48
	v_and_or_b32 v67, v64, s44, v67
	v_and_or_b32 v64, v68, s44, v105
	v_add3_u32 v105, v73, v71, s46
	v_add_f32_e32 v72, v73, v72
	v_exp_f32_e32 v73, v48
	v_sub_f32_e32 v48, v49, v161
	v_bfe_u32 v71, v74, 16, 1
	v_mul_f32_e32 v48, 0x3fb8aa3b, v48
	v_add3_u32 v71, v74, v71, s46
	v_add_f32_e32 v72, v74, v72
	v_exp_f32_e32 v74, v48
	v_sub_f32_e32 v48, v50, v161
	v_mul_f32_e32 v48, 0x3fb8aa3b, v48
	v_add_f32_e32 v72, v75, v72
	v_exp_f32_e32 v75, v48
	v_sub_f32_e32 v48, v51, v161
	v_bfe_u32 v107, v76, 16, 1
	v_mul_f32_e32 v48, 0x3fb8aa3b, v48
	v_add3_u32 v107, v76, v107, s46
	v_add_f32_e32 v72, v76, v72
	v_exp_f32_e32 v76, v48
	v_sub_f32_e32 v48, v52, v161
	v_bfe_u32 v69, v77, 16, 1
	v_mul_f32_e32 v48, 0x3fb8aa3b, v48
	v_add3_u32 v69, v77, v69, s46
	v_add_f32_e32 v72, v77, v72
	v_exp_f32_e32 v77, v48
	v_sub_f32_e32 v48, v53, v161
	v_bfe_u32 v108, v78, 16, 1
	v_mul_f32_e32 v48, 0x3fb8aa3b, v48
	v_add3_u32 v108, v78, v108, s46
	v_add_f32_e32 v72, v78, v72
	v_exp_f32_e32 v78, v48
	v_sub_f32_e32 v48, v54, v161
	v_bfe_u32 v68, v79, 16, 1
	v_mul_f32_e32 v48, 0x3fb8aa3b, v48
	v_add3_u32 v68, v79, v68, s46
	v_add_f32_e32 v72, v79, v72
	v_exp_f32_e32 v79, v48
	v_sub_f32_e32 v48, v55, v161
	v_mul_f32_e32 v48, 0x3fb8aa3b, v48
	v_exp_f32_e32 v88, v48
	v_sub_f32_e32 v48, v56, v161
	v_mul_f32_e32 v48, 0x3fb8aa3b, v48
	v_exp_f32_e32 v56, v48
	v_sub_f32_e32 v48, v57, v161
	v_mul_f32_e32 v48, 0x3fb8aa3b, v48
	v_exp_f32_e32 v57, v48
	v_sub_f32_e32 v48, v58, v161
	v_mul_f32_e32 v48, 0x3fb8aa3b, v48
	v_exp_f32_e32 v58, v48
	v_sub_f32_e32 v48, v59, v161
	v_mul_f32_e32 v48, 0x3fb8aa3b, v48
	v_exp_f32_e32 v59, v48
	v_sub_f32_e32 v48, v60, v161
	v_mul_f32_e32 v48, 0x3fb8aa3b, v48
	v_add_f32_e32 v72, v73, v72
	v_exp_f32_e32 v60, v48
	v_sub_f32_e32 v48, v61, v161
	v_add_f32_e32 v72, v74, v72
	v_mul_f32_e32 v48, 0x3fb8aa3b, v48
	v_add_f32_e32 v72, v75, v72
	v_exp_f32_e32 v61, v48
	v_sub_f32_e32 v48, v62, v161
	v_bfe_u32 v50, v76, 16, 1
	v_bfe_u32 v51, v74, 16, 1
	v_add_f32_e32 v72, v76, v72
	v_mul_f32_e32 v48, 0x3fb8aa3b, v48
	v_add3_u32 v52, v74, v51, s46
	v_add3_u32 v53, v76, v50, s46
	v_bfe_u32 v50, v73, 16, 1
	v_bfe_u32 v51, v75, 16, 1
	v_bfe_u32 v54, v77, 16, 1
	v_add_f32_e32 v72, v77, v72
	v_exp_f32_e32 v62, v48
	v_sub_f32_e32 v48, v63, v161
	v_bfe_u32 v49, v78, 16, 1
	v_add3_u32 v54, v77, v54, s46
	v_add3_u32 v51, v75, v51, s46
	v_add3_u32 v50, v73, v50, s46
	v_add_f32_e32 v72, v78, v72
	v_mul_f32_e32 v48, 0x3fb8aa3b, v48
	v_add3_u32 v49, v78, v49, s46
	v_bfe_u32 v55, v79, 16, 1
	v_lshrrev_b32_e32 v89, 16, v50
	v_lshrrev_b32_e32 v90, 16, v51
	v_lshrrev_b32_e32 v50, 16, v54
	v_bfe_u32 v54, v59, 16, 1
	v_add_f32_e32 v72, v79, v72
	v_exp_f32_e32 v63, v48
	v_bfe_u32 v48, v88, 16, 1
	v_add3_u32 v55, v79, v55, s46
	v_and_or_b32 v50, v49, s44, v50
	v_and_or_b32 v49, v53, s44, v90
	v_add3_u32 v90, v59, v54, s46
	v_bfe_u32 v54, v56, 16, 1
	v_add_f32_e32 v72, v88, v72
	v_sub_f32_e32 v32, v32, v161
	v_add3_u32 v48, v88, v48, s46
	v_lshrrev_b32_e32 v51, 16, v55
	v_bfe_u32 v55, v57, 16, 1
	v_add3_u32 v54, v56, v54, s46
	v_add_f32_e32 v56, v56, v72
	v_mul_f32_e32 v32, 0x3fb8aa3b, v32
	v_and_or_b32 v51, v48, s44, v51
	v_and_or_b32 v48, v52, s44, v89
	v_add3_u32 v89, v57, v55, s46
	v_add_f32_e32 v56, v57, v56
	v_exp_f32_e32 v57, v32
	v_sub_f32_e32 v32, v33, v161
	v_bfe_u32 v55, v58, 16, 1
	v_mul_f32_e32 v32, 0x3fb8aa3b, v32
	v_add3_u32 v55, v58, v55, s46
	v_add_f32_e32 v56, v58, v56
	v_exp_f32_e32 v58, v32
	v_sub_f32_e32 v32, v34, v161
	v_mul_f32_e32 v32, 0x3fb8aa3b, v32
	v_add_f32_e32 v56, v59, v56
	v_exp_f32_e32 v59, v32
	v_sub_f32_e32 v32, v35, v161
	v_bfe_u32 v91, v60, 16, 1
	v_mul_f32_e32 v32, 0x3fb8aa3b, v32
	v_add3_u32 v91, v60, v91, s46
	v_add_f32_e32 v56, v60, v56
	v_exp_f32_e32 v60, v32
	v_sub_f32_e32 v32, v36, v161
	v_bfe_u32 v53, v61, 16, 1
	v_mul_f32_e32 v32, 0x3fb8aa3b, v32
	v_add3_u32 v53, v61, v53, s46
	v_add_f32_e32 v56, v61, v56
	v_exp_f32_e32 v61, v32
	v_sub_f32_e32 v32, v37, v161
	v_bfe_u32 v92, v62, 16, 1
	v_mul_f32_e32 v32, 0x3fb8aa3b, v32
	v_add3_u32 v92, v62, v92, s46
	v_add_f32_e32 v56, v62, v56
	v_exp_f32_e32 v62, v32
	v_sub_f32_e32 v32, v38, v161
	v_bfe_u32 v52, v63, 16, 1
	v_mul_f32_e32 v32, 0x3fb8aa3b, v32
	v_add3_u32 v52, v63, v52, s46
	v_add_f32_e32 v56, v63, v56
	v_exp_f32_e32 v63, v32
	v_sub_f32_e32 v32, v39, v161
	v_mul_f32_e32 v32, 0x3fb8aa3b, v32
	v_exp_f32_e32 v72, v32
	v_sub_f32_e32 v32, v40, v161
	v_mul_f32_e32 v32, 0x3fb8aa3b, v32
	v_exp_f32_e32 v40, v32
	v_sub_f32_e32 v32, v41, v161
	v_mul_f32_e32 v32, 0x3fb8aa3b, v32
	v_exp_f32_e32 v41, v32
	v_sub_f32_e32 v32, v42, v161
	v_mul_f32_e32 v32, 0x3fb8aa3b, v32
	v_exp_f32_e32 v42, v32
	v_sub_f32_e32 v32, v43, v161
	v_mul_f32_e32 v32, 0x3fb8aa3b, v32
	v_exp_f32_e32 v43, v32
	v_sub_f32_e32 v32, v44, v161
	v_mul_f32_e32 v32, 0x3fb8aa3b, v32
	v_add_f32_e32 v56, v57, v56
	v_exp_f32_e32 v44, v32
	v_sub_f32_e32 v32, v45, v161
	v_add_f32_e32 v56, v58, v56
	v_mul_f32_e32 v32, 0x3fb8aa3b, v32
	v_add_f32_e32 v56, v59, v56
	v_exp_f32_e32 v45, v32
	v_sub_f32_e32 v32, v46, v161
	v_bfe_u32 v34, v60, 16, 1
	v_bfe_u32 v35, v58, 16, 1
	v_add_f32_e32 v56, v60, v56
	v_mul_f32_e32 v32, 0x3fb8aa3b, v32
	v_add3_u32 v36, v58, v35, s46
	v_add3_u32 v37, v60, v34, s46
	v_bfe_u32 v34, v57, 16, 1
	v_bfe_u32 v35, v59, 16, 1
	v_bfe_u32 v38, v61, 16, 1
	v_add_f32_e32 v56, v61, v56
	v_exp_f32_e32 v46, v32
	v_sub_f32_e32 v32, v47, v161
	v_bfe_u32 v33, v62, 16, 1
	v_add3_u32 v38, v61, v38, s46
	v_add3_u32 v35, v59, v35, s46
	v_add3_u32 v34, v57, v34, s46
	v_add_f32_e32 v56, v62, v56
	v_mul_f32_e32 v32, 0x3fb8aa3b, v32
	v_add3_u32 v33, v62, v33, s46
	v_bfe_u32 v39, v63, 16, 1
	v_lshrrev_b32_e32 v73, 16, v34
	v_lshrrev_b32_e32 v74, 16, v35
	v_lshrrev_b32_e32 v34, 16, v38
	v_bfe_u32 v38, v43, 16, 1
	v_add_f32_e32 v56, v63, v56
	v_exp_f32_e32 v47, v32
	v_bfe_u32 v32, v72, 16, 1
	v_add3_u32 v39, v63, v39, s46
	v_and_or_b32 v34, v33, s44, v34
	v_and_or_b32 v33, v37, s44, v74
	v_add3_u32 v74, v43, v38, s46
	v_bfe_u32 v38, v40, 16, 1
	v_add_f32_e32 v56, v72, v56
	v_sub_f32_e32 v16, v16, v161
	v_add3_u32 v32, v72, v32, s46
	v_lshrrev_b32_e32 v35, 16, v39
	v_bfe_u32 v39, v41, 16, 1
	v_add3_u32 v38, v40, v38, s46
	v_add_f32_e32 v40, v40, v56
	v_mul_f32_e32 v16, 0x3fb8aa3b, v16
	v_and_or_b32 v35, v32, s44, v35
	v_and_or_b32 v32, v36, s44, v73
	v_add3_u32 v73, v41, v39, s46
	v_add_f32_e32 v40, v41, v40
	v_exp_f32_e32 v41, v16
	v_sub_f32_e32 v16, v17, v161
	v_bfe_u32 v39, v42, 16, 1
	v_mul_f32_e32 v16, 0x3fb8aa3b, v16
	v_add3_u32 v39, v42, v39, s46
	v_add_f32_e32 v40, v42, v40
	v_exp_f32_e32 v42, v16
	v_sub_f32_e32 v16, v18, v161
	v_mul_f32_e32 v16, 0x3fb8aa3b, v16
	v_add_f32_e32 v40, v43, v40
	v_exp_f32_e32 v43, v16
	v_sub_f32_e32 v16, v19, v161
	v_bfe_u32 v75, v44, 16, 1
	v_mul_f32_e32 v16, 0x3fb8aa3b, v16
	v_add3_u32 v75, v44, v75, s46
	v_add_f32_e32 v40, v44, v40
	v_exp_f32_e32 v44, v16
	v_sub_f32_e32 v16, v20, v161
	v_bfe_u32 v37, v45, 16, 1
	v_mul_f32_e32 v16, 0x3fb8aa3b, v16
	v_add3_u32 v37, v45, v37, s46
	v_add_f32_e32 v40, v45, v40
	v_exp_f32_e32 v45, v16
	v_sub_f32_e32 v16, v21, v161
	v_bfe_u32 v76, v46, 16, 1
	v_mul_f32_e32 v16, 0x3fb8aa3b, v16
	v_add3_u32 v76, v46, v76, s46
	v_add_f32_e32 v40, v46, v40
	v_exp_f32_e32 v46, v16
	v_sub_f32_e32 v16, v22, v161
	v_bfe_u32 v36, v47, 16, 1
	v_mul_f32_e32 v16, 0x3fb8aa3b, v16
	v_add3_u32 v36, v47, v36, s46
	v_add_f32_e32 v40, v47, v40
	v_exp_f32_e32 v47, v16
	v_sub_f32_e32 v16, v23, v161
	v_mul_f32_e32 v16, 0x3fb8aa3b, v16
	v_exp_f32_e32 v56, v16
	v_sub_f32_e32 v16, v24, v161
	v_mul_f32_e32 v16, 0x3fb8aa3b, v16
	v_exp_f32_e32 v24, v16
	v_sub_f32_e32 v16, v25, v161
	v_mul_f32_e32 v16, 0x3fb8aa3b, v16
	v_exp_f32_e32 v25, v16
	v_sub_f32_e32 v16, v26, v161
	v_mul_f32_e32 v16, 0x3fb8aa3b, v16
	v_exp_f32_e32 v26, v16
	v_sub_f32_e32 v16, v27, v161
	v_add_f32_e32 v40, v41, v40
	v_mul_f32_e32 v16, 0x3fb8aa3b, v16
	v_add_f32_e32 v40, v42, v40
	v_exp_f32_e32 v27, v16
	v_add_f32_e32 v40, v43, v40
	v_sub_f32_e32 v16, v28, v161
	v_bfe_u32 v18, v44, 16, 1
	v_bfe_u32 v19, v42, 16, 1
	v_add_f32_e32 v40, v44, v40
	v_mul_f32_e32 v16, 0x3fb8aa3b, v16
	v_add3_u32 v20, v42, v19, s46
	v_add3_u32 v21, v44, v18, s46
	v_bfe_u32 v18, v41, 16, 1
	v_bfe_u32 v19, v43, 16, 1
	v_bfe_u32 v22, v45, 16, 1
	v_add_f32_e32 v40, v45, v40
	v_exp_f32_e32 v28, v16
	v_sub_f32_e32 v16, v29, v161
	v_bfe_u32 v17, v46, 16, 1
	v_add3_u32 v22, v45, v22, s46
	v_add3_u32 v19, v43, v19, s46
	v_add3_u32 v18, v41, v18, s46
	v_add_f32_e32 v40, v46, v40
	v_mul_f32_e32 v16, 0x3fb8aa3b, v16
	v_add3_u32 v17, v46, v17, s46
	v_lshrrev_b32_e32 v57, 16, v18
	v_lshrrev_b32_e32 v58, 16, v19
	v_lshrrev_b32_e32 v18, 16, v22
	v_bfe_u32 v22, v27, 16, 1
	v_add_f32_e32 v40, v47, v40
	v_exp_f32_e32 v29, v16
	v_sub_f32_e32 v16, v30, v161
	v_and_or_b32 v18, v17, s44, v18
	v_and_or_b32 v17, v21, s44, v58
	v_add3_u32 v58, v27, v22, s46
	v_bfe_u32 v22, v24, 16, 1
	v_add_f32_e32 v40, v56, v40
	v_mul_f32_e32 v16, 0x3fb8aa3b, v16
	v_add3_u32 v22, v24, v22, s46
	v_add_f32_e32 v24, v24, v40
	v_sub_f32_e32 v3, v3, v161
	v_exp_f32_e32 v30, v16
	v_sub_f32_e32 v16, v31, v161
	v_add_f32_e32 v24, v25, v24
	v_sub_f32_e32 v0, v0, v161
	v_mul_f32_e32 v3, 0x3fb8aa3b, v3
	v_mul_f32_e32 v16, 0x3fb8aa3b, v16
	v_bfe_u32 v23, v47, 16, 1
	v_add_f32_e32 v24, v26, v24
	v_mul_f32_e32 v0, 0x3fb8aa3b, v0
	v_exp_f32_e32 v3, v3
	v_exp_f32_e32 v31, v16
	v_bfe_u32 v16, v56, 16, 1
	v_add3_u32 v23, v47, v23, s46
	v_add_f32_e32 v24, v27, v24
	v_exp_f32_e32 v0, v0
	v_sub_f32_e32 v1, v1, v161
	v_add3_u32 v16, v56, v16, s46
	v_lshrrev_b32_e32 v19, 16, v23
	v_bfe_u32 v23, v25, 16, 1
	v_add_f32_e32 v24, v28, v24
	v_mul_f32_e32 v1, 0x3fb8aa3b, v1
	v_sub_f32_e32 v2, v2, v161
	v_and_or_b32 v19, v16, s44, v19
	v_and_or_b32 v16, v20, s44, v57
	v_add3_u32 v57, v25, v23, s46
	v_bfe_u32 v23, v26, 16, 1
	v_add_f32_e32 v24, v29, v24
	v_exp_f32_e32 v1, v1
	v_mul_f32_e32 v2, 0x3fb8aa3b, v2
	v_bfe_u32 v59, v28, 16, 1
	v_bfe_u32 v60, v30, 16, 1
	v_add3_u32 v23, v26, v23, s46
	v_add_f32_e32 v24, v30, v24
	v_exp_f32_e32 v2, v2
	v_sub_f32_e32 v4, v4, v161
	v_bfe_u32 v26, v3, 16, 1
	v_add3_u32 v60, v30, v60, s46
	v_add3_u32 v59, v28, v59, s46
	v_add_f32_e32 v28, v31, v24
	v_mul_f32_e32 v4, 0x3fb8aa3b, v4
	v_sub_f32_e32 v5, v5, v161
	v_add3_u32 v30, v3, v26, s46
	v_bfe_u32 v26, v0, 16, 1
	v_exp_f32_e32 v4, v4
	v_mul_f32_e32 v5, 0x3fb8aa3b, v5
	v_sub_f32_e32 v6, v6, v161
	v_add3_u32 v26, v0, v26, s46
	v_add_f32_e32 v0, v0, v28
	v_exp_f32_e32 v5, v5
	v_mul_f32_e32 v6, 0x3fb8aa3b, v6
	v_sub_f32_e32 v7, v7, v161
	v_add_f32_e32 v0, v1, v0
	v_exp_f32_e32 v6, v6
	v_mul_f32_e32 v7, 0x3fb8aa3b, v7
	v_sub_f32_e32 v8, v8, v161
	v_add_f32_e32 v0, v2, v0
	v_exp_f32_e32 v7, v7
	v_mul_f32_e32 v8, 0x3fb8aa3b, v8
	v_sub_f32_e32 v9, v9, v161
	v_add_f32_e32 v0, v3, v0
	v_exp_f32_e32 v8, v8
	v_mul_f32_e32 v9, 0x3fb8aa3b, v9
	v_sub_f32_e32 v10, v10, v161
	v_add_f32_e32 v0, v4, v0
	v_exp_f32_e32 v9, v9
	v_mul_f32_e32 v10, 0x3fb8aa3b, v10
	v_sub_f32_e32 v11, v11, v161
	v_add_f32_e32 v0, v5, v0
	v_exp_f32_e32 v10, v10
	v_mul_f32_e32 v11, 0x3fb8aa3b, v11
	v_sub_f32_e32 v12, v12, v161
	v_add_f32_e32 v0, v6, v0
	v_exp_f32_e32 v11, v11
	v_mul_f32_e32 v12, 0x3fb8aa3b, v12
	v_sub_f32_e32 v13, v13, v161
	v_add_f32_e32 v0, v7, v0
	v_exp_f32_e32 v12, v12
	v_mul_f32_e32 v13, 0x3fb8aa3b, v13
	v_sub_f32_e32 v14, v14, v161
	v_add_f32_e32 v0, v8, v0
	v_exp_f32_e32 v13, v13
	v_mul_f32_e32 v14, 0x3fb8aa3b, v14
	v_sub_f32_e32 v15, v15, v161
	v_add_f32_e32 v0, v9, v0
	v_exp_f32_e32 v14, v14
	v_mul_f32_e32 v15, 0x3fb8aa3b, v15
	v_add_f32_e32 v0, v10, v0
	v_exp_f32_e32 v15, v15
	v_add_f32_e32 v0, v11, v0
	v_add_f32_e32 v0, v12, v0
	v_add_f32_e32 v0, v13, v0
	v_add_f32_e32 v0, v14, v0
	v_bfe_u32 v21, v29, 16, 1
	v_bfe_u32 v27, v1, 16, 1
	v_add_f32_e32 v0, v15, v0
	v_add3_u32 v21, v29, v21, s46
	v_add3_u32 v29, v1, v27, s46
	ds_bpermute_b32 v1, v159, v0
	v_bfe_u32 v20, v31, 16, 1
	v_bfe_u32 v27, v2, 16, 1
	v_bfe_u32 v40, v6, 16, 1
	v_add3_u32 v20, v31, v20, s46
	s_waitcnt lgkmcnt(0)
	v_add_f32_e32 v210, v0, v1
	v_and_or_b32 v0, v211, 60, v138
	v_lshlrev_b32_e32 v0, 2, v0
	ds_bpermute_b32 v1, v0, v210
	v_bfe_u32 v24, v7, 16, 1
	v_bfe_u32 v31, v4, 16, 1
	v_add3_u32 v40, v6, v40, s46
	v_add3_u32 v27, v2, v27, s46
	v_add3_u32 v24, v7, v24, s46
	v_add3_u32 v31, v4, v31, s46
	v_lshrrev_b32_e32 v41, 16, v26
	v_lshrrev_b32_e32 v42, 16, v27
	v_lshrrev_b32_e32 v27, 16, v40
	v_bfe_u32 v44, v14, 16, 1
	v_bfe_u32 v25, v5, 16, 1
	v_lshrrev_b32_e32 v26, 16, v31
	v_and_or_b32 v27, v24, s44, v27
	v_and_or_b32 v24, v29, s44, v41
	v_bfe_u32 v29, v15, 16, 1
	v_bfe_u32 v31, v11, 16, 1
	v_add3_u32 v44, v14, v44, s46
	v_add3_u32 v25, v5, v25, s46
	v_add3_u32 v41, v11, v31, s46
	v_add3_u32 v29, v15, v29, s46
	v_bfe_u32 v31, v8, 16, 1
	v_lshrrev_b32_e32 v5, 16, v44
	v_add3_u32 v3, v8, v31, s46
	v_and_or_b32 v31, v29, s44, v5
	s_waitcnt lgkmcnt(0)
	v_div_scale_f32 v5, s[58:59], v1, v1, 1.0
	v_rcp_f32_e32 v6, v5
	v_and_or_b32 v26, v25, s44, v26
	v_and_or_b32 v25, v30, s44, v42
	v_bfe_u32 v42, v10, 16, 1
	v_bfe_u32 v43, v12, 16, 1
	v_bfe_u32 v30, v13, 16, 1
	v_add3_u32 v43, v12, v43, s46
	v_add3_u32 v2, v10, v42, s46
	v_add3_u32 v30, v13, v30, s46
	v_lshrrev_b32_e32 v2, 16, v2
	v_lshrrev_b32_e32 v4, 16, v43
	v_bfe_u32 v40, v9, 16, 1
	v_and_or_b32 v30, v30, s44, v4
	v_and_or_b32 v29, v41, s44, v2
	v_fma_f32 v2, -v5, v6, 1.0
	ds_bpermute_b32 v4, v0, v210 offset:4
	v_add3_u32 v40, v9, v40, s46
	v_lshrrev_b32_e32 v3, 16, v3
	v_fmac_f32_e32 v6, v2, v6
	v_div_scale_f32 v2, vcc, 1.0, v1, 1.0
	v_and_or_b32 v28, v40, s44, v3
	v_mul_f32_e32 v3, v2, v6
	v_fma_f32 v7, -v5, v3, v2
	v_fmac_f32_e32 v3, v7, v6
	v_fma_f32 v2, -v5, v3, v2
	s_waitcnt lgkmcnt(0)
	v_div_scale_f32 v5, s[58:59], v4, v4, 1.0
	v_rcp_f32_e32 v7, v5
	v_div_fmas_f32 v2, v2, v6, v3
	v_div_fixup_f32 v40, v2, v1, 1.0
	ds_bpermute_b32 v3, v0, v210 offset:8
	v_fma_f32 v1, -v5, v7, 1.0
	v_fmac_f32_e32 v7, v1, v7
	v_div_scale_f32 v1, vcc, 1.0, v4, 1.0
	v_mul_f32_e32 v2, v1, v7
	v_fma_f32 v6, -v5, v2, v1
	v_fmac_f32_e32 v2, v6, v7
	v_fma_f32 v1, -v5, v2, v1
	s_waitcnt lgkmcnt(0)
	v_div_scale_f32 v5, s[58:59], v3, v3, 1.0
	v_rcp_f32_e32 v6, v5
	v_div_fmas_f32 v1, v1, v7, v2
	v_div_fixup_f32 v41, v1, v4, 1.0
	ds_bpermute_b32 v0, v0, v210 offset:12
	v_fma_f32 v1, -v5, v6, 1.0
	v_fmac_f32_e32 v6, v1, v6
	v_div_scale_f32 v1, vcc, 1.0, v3, 1.0
	v_mul_f32_e32 v2, v1, v6
	v_fma_f32 v4, -v5, v2, v1
	v_fmac_f32_e32 v2, v4, v6
	v_fma_f32 v1, -v5, v2, v1
	s_waitcnt lgkmcnt(0)
	v_div_scale_f32 v4, s[58:59], v0, v0, 1.0
	v_rcp_f32_e32 v5, v4
	v_div_fmas_f32 v1, v1, v6, v2
	v_div_fixup_f32 v42, v1, v3, 1.0
	v_add_u32_e32 v3, 8, v211
	v_and_or_b32 v3, v3, 60, v138
	v_lshlrev_b32_e32 v3, 2, v3
	v_fma_f32 v1, -v4, v5, 1.0
	ds_bpermute_b32 v3, v3, v210
	v_fmac_f32_e32 v5, v1, v5
	v_div_scale_f32 v1, vcc, 1.0, v0, 1.0
	v_mul_f32_e32 v2, v1, v5
	v_fma_f32 v6, -v4, v2, v1
	v_fmac_f32_e32 v2, v6, v5
	v_fma_f32 v1, -v4, v2, v1
	s_waitcnt lgkmcnt(0)
	v_div_scale_f32 v4, s[58:59], v3, v3, 1.0
	v_rcp_f32_e32 v6, v4
	v_div_fmas_f32 v1, v1, v5, v2
	v_add_u32_e32 v2, 9, v211
	v_and_or_b32 v2, v2, 61, v138
	v_lshlrev_b32_e32 v2, 2, v2
	v_div_fixup_f32 v43, v1, v0, 1.0
	v_fma_f32 v0, -v4, v6, 1.0
	ds_bpermute_b32 v2, v2, v210
	v_fmac_f32_e32 v6, v0, v6
	v_div_scale_f32 v0, vcc, 1.0, v3, 1.0
	v_mul_f32_e32 v1, v0, v6
	v_fma_f32 v5, -v4, v1, v0
	v_fmac_f32_e32 v1, v5, v6
	v_fma_f32 v0, -v4, v1, v0
	s_waitcnt lgkmcnt(0)
	v_div_scale_f32 v4, s[58:59], v2, v2, 1.0
	v_rcp_f32_e32 v5, v4
	v_div_fmas_f32 v0, v0, v6, v1
	v_div_fixup_f32 v44, v0, v3, 1.0
	v_add_u32_e32 v3, 10, v211
	v_and_or_b32 v3, v3, 62, v138
	v_lshlrev_b32_e32 v3, 2, v3
	v_fma_f32 v0, -v4, v5, 1.0
	ds_bpermute_b32 v3, v3, v210
	v_fmac_f32_e32 v5, v0, v5
	v_div_scale_f32 v0, vcc, 1.0, v2, 1.0
	v_mul_f32_e32 v1, v0, v5
	v_fma_f32 v6, -v4, v1, v0
	v_fmac_f32_e32 v1, v6, v5
	v_fma_f32 v0, -v4, v1, v0
	s_waitcnt lgkmcnt(0)
	v_div_scale_f32 v4, s[58:59], v3, v3, 1.0
	v_rcp_f32_e32 v6, v4
	v_div_fmas_f32 v0, v0, v5, v1
	v_div_fixup_f32 v45, v0, v2, 1.0
	v_add_u32_e32 v2, 11, v211
	v_and_or_b32 v2, v2, 63, v138
	v_lshlrev_b32_e32 v2, 2, v2
	v_fma_f32 v0, -v4, v6, 1.0
	ds_bpermute_b32 v2, v2, v210
	v_fmac_f32_e32 v6, v0, v6
	v_div_scale_f32 v0, vcc, 1.0, v3, 1.0
	v_mul_f32_e32 v1, v0, v6
	v_fma_f32 v5, -v4, v1, v0
	v_fmac_f32_e32 v1, v5, v6
	v_fma_f32 v0, -v4, v1, v0
	s_waitcnt lgkmcnt(0)
	v_div_scale_f32 v4, s[58:59], v2, v2, 1.0
	v_rcp_f32_e32 v5, v4
	v_div_fmas_f32 v0, v0, v6, v1
	v_div_fixup_f32 v46, v0, v3, 1.0
	v_add_u32_e32 v3, 16, v211
	v_and_or_b32 v3, v3, 60, v138
	v_lshlrev_b32_e32 v3, 2, v3
	v_fma_f32 v0, -v4, v5, 1.0
	ds_bpermute_b32 v3, v3, v210
	v_fmac_f32_e32 v5, v0, v5
	v_div_scale_f32 v0, vcc, 1.0, v2, 1.0
	v_mul_f32_e32 v1, v0, v5
	v_fma_f32 v6, -v4, v1, v0
	v_fmac_f32_e32 v1, v6, v5
	v_fma_f32 v0, -v4, v1, v0
	s_waitcnt lgkmcnt(0)
	v_div_scale_f32 v4, s[58:59], v3, v3, 1.0
	v_rcp_f32_e32 v6, v4
	v_div_fmas_f32 v0, v0, v5, v1
	v_div_fixup_f32 v47, v0, v2, 1.0
	v_add_u32_e32 v2, 17, v211
	v_and_or_b32 v2, v2, 61, v138
	v_lshlrev_b32_e32 v2, 2, v2
	v_fma_f32 v0, -v4, v6, 1.0
	ds_bpermute_b32 v2, v2, v210
	v_fmac_f32_e32 v6, v0, v6
	v_div_scale_f32 v0, vcc, 1.0, v3, 1.0
	v_mul_f32_e32 v1, v0, v6
	v_fma_f32 v5, -v4, v1, v0
	v_fmac_f32_e32 v1, v5, v6
	v_fma_f32 v0, -v4, v1, v0
	s_waitcnt lgkmcnt(0)
	v_div_scale_f32 v4, s[58:59], v2, v2, 1.0
	v_rcp_f32_e32 v5, v4
	v_div_fmas_f32 v0, v0, v6, v1
	v_div_fixup_f32 v56, v0, v3, 1.0
	v_add_u32_e32 v3, 18, v211
	v_and_or_b32 v3, v3, 62, v138
	v_lshlrev_b32_e32 v3, 2, v3
	v_fma_f32 v0, -v4, v5, 1.0
	ds_bpermute_b32 v3, v3, v210
	v_fmac_f32_e32 v5, v0, v5
	v_div_scale_f32 v0, vcc, 1.0, v2, 1.0
	v_mul_f32_e32 v1, v0, v5
	v_fma_f32 v6, -v4, v1, v0
	v_fmac_f32_e32 v1, v6, v5
	v_fma_f32 v0, -v4, v1, v0
	s_waitcnt lgkmcnt(0)
	v_div_scale_f32 v4, s[58:59], v3, v3, 1.0
	v_lshrrev_b32_e32 v61, 16, v22
	v_lshrrev_b32_e32 v62, 16, v23
	v_lshrrev_b32_e32 v23, 16, v60
	v_rcp_f32_e32 v6, v4
	v_div_fmas_f32 v0, v0, v5, v1
	v_and_or_b32 v23, v20, s44, v23
	v_and_or_b32 v20, v57, s44, v61
	v_div_fixup_f32 v57, v0, v2, 1.0
	v_add_u32_e32 v2, 19, v211
	v_and_or_b32 v2, v2, 63, v138
	v_lshlrev_b32_e32 v2, 2, v2
	v_fma_f32 v0, -v4, v6, 1.0
	ds_bpermute_b32 v2, v2, v210
	v_fmac_f32_e32 v6, v0, v6
	v_div_scale_f32 v0, vcc, 1.0, v3, 1.0
	v_mul_f32_e32 v1, v0, v6
	v_fma_f32 v5, -v4, v1, v0
	v_fmac_f32_e32 v1, v5, v6
	v_fma_f32 v0, -v4, v1, v0
	s_waitcnt lgkmcnt(0)
	v_div_scale_f32 v4, s[58:59], v2, v2, 1.0
	v_rcp_f32_e32 v5, v4
	v_lshrrev_b32_e32 v22, 16, v59
	v_div_fmas_f32 v0, v0, v6, v1
	v_and_or_b32 v22, v21, s44, v22
	v_and_or_b32 v21, v58, s44, v62
	v_div_fixup_f32 v58, v0, v3, 1.0
	v_fma_f32 v0, -v4, v5, 1.0
	v_add_u32_e32 v3, 24, v211
	v_fmac_f32_e32 v5, v0, v5
	v_div_scale_f32 v0, vcc, 1.0, v2, 1.0
	v_and_or_b32 v3, v3, 60, v138
	v_mul_f32_e32 v1, v0, v5
	v_lshlrev_b32_e32 v3, 2, v3
	ds_bpermute_b32 v212, v3, v210
	v_fma_f32 v3, -v4, v1, v0
	v_fmac_f32_e32 v1, v3, v5
	v_lshrrev_b32_e32 v175, 16, v102
	v_lshrrev_b32_e32 v179, 16, v103
	v_lshrrev_b32_e32 v102, 16, v169
	v_lshrrev_b32_e32 v103, 16, v171
	v_fma_f32 v0, -v4, v1, v0
	v_lshrrev_b32_e32 v191, 16, v118
	v_lshrrev_b32_e32 v206, 16, v119
	v_lshrrev_b32_e32 v119, 16, v189
	v_and_or_b32 v103, v100, s44, v103
	v_and_or_b32 v102, v101, s44, v102
	v_and_or_b32 v101, v167, s44, v179
	v_and_or_b32 v100, v165, s44, v175
	v_lshrrev_b32_e32 v77, 16, v38
	v_lshrrev_b32_e32 v78, 16, v39
	v_lshrrev_b32_e32 v39, 16, v76
	v_div_fmas_f32 v0, v0, v5, v1
	v_lshl_add_u64 v[60:61], s[36:37], 1, v[154:155]
	v_mov_b32_e32 v171, v139
	v_mov_b32_e32 v175, v139
	v_mov_b32_e32 v179, v139
	v_mov_b32_e32 v159, v139
	v_mov_b32_e32 v181, v139
	v_lshrrev_b32_e32 v118, 16, v187
	v_and_or_b32 v119, v116, s44, v119
	v_and_or_b32 v116, v183, s44, v191
	v_lshrrev_b32_e32 v93, 16, v54
	v_lshrrev_b32_e32 v94, 16, v55
	v_lshrrev_b32_e32 v55, 16, v92
	v_lshrrev_b32_e32 v38, 16, v75
	v_and_or_b32 v39, v36, s44, v39
	v_and_or_b32 v36, v73, s44, v77
	v_div_fixup_f32 v59, v0, v2, 1.0
	v_lshl_add_u64 v[0:1], v[60:61], 0, v[170:171]
	v_lshl_add_u64 v[4:5], v[60:61], 0, v[174:175]
	v_lshl_add_u64 v[8:9], v[60:61], 0, v[156:157]
	v_lshl_add_u64 v[12:13], v[60:61], 0, v[178:179]
	v_lshl_add_u64 v[62:63], v[60:61], 0, v[158:159]
	v_lshl_add_u64 v[76:77], v[60:61], 0, v[180:181]
	v_mov_b32_e32 v161, v139
	v_mov_b32_e32 v183, v139
	v_and_or_b32 v118, v117, s44, v118
	v_and_or_b32 v117, v185, s44, v206
	v_lshrrev_b32_e32 v109, 16, v70
	v_lshrrev_b32_e32 v110, 16, v71
	v_lshrrev_b32_e32 v71, 16, v108
	v_lshrrev_b32_e32 v54, 16, v91
	v_and_or_b32 v55, v52, s44, v55
	v_and_or_b32 v52, v89, s44, v93
	v_and_or_b32 v38, v37, s44, v38
	v_and_or_b32 v37, v74, s44, v78
	global_load_dwordx4 v[0:3], v[0:1], off
	s_nop 0
	global_load_dwordx4 v[4:7], v[4:5], off
	s_nop 0
	global_load_dwordx4 v[8:11], v[8:9], off
	s_nop 0
	global_load_dwordx4 v[12:15], v[12:13], off
	s_nop 0
	global_load_dwordx4 v[72:75], v[62:63], off
	s_nop 0
	global_load_dwordx4 v[76:79], v[76:77], off
	v_lshl_add_u64 v[62:63], v[60:61], 0, v[160:161]
	v_lshl_add_u64 v[92:93], v[60:61], 0, v[182:183]
	v_mov_b32_e32 v163, v139
	v_mov_b32_e32 v185, v139
	v_lshrrev_b32_e32 v125, 16, v86
	v_lshrrev_b32_e32 v126, 16, v87
	v_lshrrev_b32_e32 v87, 16, v124
	v_lshrrev_b32_e32 v70, 16, v107
	v_and_or_b32 v71, v68, s44, v71
	v_and_or_b32 v68, v105, s44, v109
	v_and_or_b32 v54, v53, s44, v54
	v_and_or_b32 v53, v90, s44, v94
	global_load_dwordx4 v[88:91], v[62:63], off
	s_nop 0
	global_load_dwordx4 v[92:95], v[92:93], off
	v_lshl_add_u64 v[62:63], v[60:61], 0, v[162:163]
	v_lshl_add_u64 v[108:109], v[60:61], 0, v[184:185]
	v_mov_b32_e32 v165, v139
	v_mov_b32_e32 v187, v139
	v_lshrrev_b32_e32 v86, 16, v123
	v_and_or_b32 v87, v84, s44, v87
	v_and_or_b32 v84, v121, s44, v125
	v_and_or_b32 v70, v69, s44, v70
	v_and_or_b32 v69, v106, s44, v110
	global_load_dwordx4 v[104:107], v[62:63], off
	s_nop 0
	global_load_dwordx4 v[108:111], v[108:109], off
	v_lshl_add_u64 v[62:63], v[60:61], 0, v[164:165]
	v_lshl_add_u64 v[124:125], v[60:61], 0, v[186:187]
	v_mov_b32_e32 v167, v139
	v_mov_b32_e32 v189, v139
	v_and_or_b32 v86, v85, s44, v86
	v_and_or_b32 v85, v122, s44, v126
	global_load_dwordx4 v[120:123], v[62:63], off
	s_nop 0
	global_load_dwordx4 v[124:127], v[124:125], off
	v_lshl_add_u64 v[62:63], v[60:61], 0, v[166:167]
	v_lshl_add_u64 v[184:185], v[60:61], 0, v[188:189]
	v_mov_b32_e32 v169, v139
	global_load_dwordx4 v[180:183], v[62:63], off
	s_nop 0
	global_load_dwordx4 v[184:187], v[184:185], off
	v_lshl_add_u64 v[62:63], v[60:61], 0, v[168:169]
	v_mov_b32_e32 v191, v139
	v_lshl_add_u64 v[60:61], v[60:61], 0, v[190:191]
	global_load_dwordx4 v[188:191], v[62:63], off
	global_load_dwordx4 v[206:209], v[60:61], off
	s_waitcnt lgkmcnt(0)
	v_div_scale_f32 v213, s[58:59], v212, v212, 1.0
	v_rcp_f32_e32 v214, v213
	v_add_u32_e32 v62, 25, v211
	v_and_or_b32 v62, v62, 61, v138
	v_lshlrev_b32_e32 v62, 2, v62
	ds_bpermute_b32 v62, v62, v210
	v_fma_f32 v215, -v213, v214, 1.0
	v_fmac_f32_e32 v214, v215, v214
	v_div_scale_f32 v60, vcc, 1.0, v212, 1.0
	v_mul_f32_e32 v61, v60, v214
	v_fma_f32 v63, -v213, v61, v60
	v_fmac_f32_e32 v61, v63, v214
	s_waitcnt lgkmcnt(0)
	v_div_scale_f32 v63, s[36:37], v62, v62, 1.0
	v_rcp_f32_e32 v157, v63
	v_add_u32_e32 v161, 26, v211
	v_and_or_b32 v161, v161, 62, v138
	v_fma_f32 v60, -v213, v61, v60
	v_lshlrev_b32_e32 v161, 2, v161
	v_div_fmas_f32 v60, v60, v214, v61
	v_fma_f32 v61, -v63, v157, 1.0
	ds_bpermute_b32 v161, v161, v210
	v_fmac_f32_e32 v157, v61, v157
	v_div_scale_f32 v61, vcc, 1.0, v62, 1.0
	v_mul_f32_e32 v159, v61, v157
	v_fma_f32 v163, -v63, v159, v61
	v_fmac_f32_e32 v159, v163, v157
	v_fma_f32 v61, -v63, v159, v61
	s_waitcnt lgkmcnt(0)
	v_div_scale_f32 v63, s[36:37], v161, v161, 1.0
	v_rcp_f32_e32 v163, v63
	v_div_fmas_f32 v61, v61, v157, v159
	v_add_u32_e32 v159, 27, v211
	v_and_or_b32 v138, v159, 63, v138
	v_lshlrev_b32_e32 v138, 2, v138
	v_div_fixup_f32 v61, v61, v62, 1.0
	v_fma_f32 v62, -v63, v163, 1.0
	ds_bpermute_b32 v138, v138, v210
	v_fmac_f32_e32 v163, v62, v163
	v_div_scale_f32 v62, vcc, 1.0, v161, 1.0
	v_mul_f32_e32 v157, v62, v163
	v_fma_f32 v159, -v63, v157, v62
	v_fmac_f32_e32 v157, v159, v163
	v_fma_f32 v62, -v63, v157, v62
	s_waitcnt lgkmcnt(0)
	v_div_scale_f32 v63, s[36:37], v138, v138, 1.0
	v_rcp_f32_e32 v159, v63
	v_div_fmas_f32 v62, v62, v163, v157
	s_add_u32 s57, s28, s14
	s_addc_u32 s58, s29, 0
	v_fma_f32 v157, -v63, v159, 1.0
	v_fmac_f32_e32 v159, v157, v159
	v_div_scale_f32 v157, vcc, 1.0, v138, 1.0
	s_lshl_b64 s[18:19], s[18:19], 22
	s_lshr_b32 s36, s56, 6
	s_mov_b32 s37, s15
	v_div_fixup_f32 v62, v62, v161, 1.0
	v_mul_f32_e32 v161, v157, v159
	s_or_b32 s18, s18, s39
	s_lshl_b64 s[36:37], s[36:37], 16
	v_fma_f32 v163, -v63, v161, v157
	s_add_u32 s18, s18, s36
	v_fmac_f32_e32 v161, v163, v159
	s_addc_u32 s19, s19, s37
	v_fma_f32 v63, -v63, v161, v157
	s_or_b64 s[18:19], s[18:19], s[14:15]
	v_div_fmas_f32 v63, v63, v159, v161
	s_add_u32 s14, s28, s18
	s_mov_b32 s38, 0
	v_div_fixup_f32 v60, v60, v212, 1.0
	v_div_fixup_f32 v63, v63, v138, 1.0
	s_addc_u32 s39, s29, s19
	s_mov_b64 s[18:19], 0
	s_mov_b32 s56, 0
	s_waitcnt vmcnt(15)
	ds_write_b128 v137, v[0:3]
	s_waitcnt vmcnt(14)
	ds_write_b128 v197, v[4:7]
	s_waitcnt vmcnt(13)
	ds_write_b128 v137, v[8:11] offset:8192
	s_waitcnt vmcnt(12)
	ds_write_b128 v198, v[12:15]
	s_waitcnt vmcnt(11)
	ds_write_b128 v137, v[72:75] offset:16384
	s_waitcnt vmcnt(10)
	ds_write_b128 v199, v[76:79]
	s_waitcnt vmcnt(9)
	ds_write_b128 v137, v[88:91] offset:24576
	s_waitcnt vmcnt(8)
	ds_write_b128 v200, v[92:95]
	s_waitcnt vmcnt(7)
	ds_write_b128 v137, v[104:107] offset:32768
	s_waitcnt vmcnt(6)
	ds_write_b128 v201, v[108:111]
	s_waitcnt vmcnt(5)
	ds_write_b128 v137, v[120:123] offset:40960
	s_waitcnt vmcnt(4)
	ds_write_b128 v202, v[124:127]
	s_waitcnt vmcnt(3)
	ds_write_b128 v137, v[180:183] offset:49152
	s_waitcnt vmcnt(2)
	ds_write_b128 v203, v[184:187]
	s_waitcnt vmcnt(1)
	ds_write_b128 v137, v[188:191] offset:57344
	s_waitcnt vmcnt(0)
	ds_write_b128 v204, v[206:209]
	s_waitcnt lgkmcnt(0)
	s_barrier
